# W_down column maxima moved from the out-proj (P4) side job into the in-proj (P1) side job range; P4 runs its side-job-free loop only and its empty final flush is gone
# baseline (speedup 1.0000x reference)
.LBB0_163:
	s_or_b64 exec, exec, s[4:5]
	s_abs_i32 s11, s94
	s_waitcnt lgkmcnt(0)
	v_cvt_f32_u32_e32 v0, s11
	s_sub_i32 s8, 0, s11
	s_add_i32 s3, s94, 0x80fff
	s_sub_i32 s5, 0xfff7f001, s94
	v_rcp_iflag_f32_e32 v0, v0
	s_max_i32 s5, s3, s5
	s_ashr_i32 s4, s3, 31
	s_ashr_i32 s95, s94, 31
	v_mul_f32_e32 v0, 0x4f7ffffe, v0
	v_cvt_u32_f32_e32 v0, v0
	s_xor_b32 s4, s4, s95
	v_mov_b32_e32 v172, v234
	s_mov_b32 s3, 0
	v_readfirstlane_b32 s9, v0
	s_mul_i32 s8, s8, s9
	s_mul_hi_u32 s8, s9, s8
	s_add_i32 s8, s9, s8
	v_writelane_b32 v254, s8, 10
	s_mul_hi_u32 s8, s5, s8
	s_mul_i32 s9, s8, s11
	s_sub_i32 s5, s5, s9
	s_add_i32 s9, s8, 1
	s_sub_i32 s10, s5, s11
	s_cmp_ge_u32 s5, s11
	s_cselect_b32 s8, s9, s8
	s_cselect_b32 s5, s10, s5
	s_add_i32 s9, s8, 1
	s_cmp_ge_u32 s5, s11
	s_cselect_b32 s5, s9, s8
	s_xor_b32 s5, s5, s4
	s_sub_i32 s4, s5, s4
	s_and_b32 s5, s4, 1
	s_add_i32 s4, s5, s4
	s_mul_i32 s8, s4, s80
	s_sub_i32 s5, 0x81000, s8
	s_min_i32 s4, s5, s4
	s_cmp_lt_i32 s8, 0x81001
	s_cselect_b32 s22, s4, 0
	v_writelane_b32 v254, s11, 11
	s_cmp_eq_u32 s22, 0
	s_mov_b32 s33, 1
	s_barrier
	s_cbranch_scc1 .LBB0_168
	s_cmp_gt_i32 s8, 0x55fff
	s_cbranch_scc0 .LBB0_166
	s_add_i32 s3, s8, 0xfffaa000
	s_mul_hi_u32 s4, s3, 0x2fa0be83
	s_lshr_b32 s4, s4, 11
	s_mul_i32 s5, s4, 0xffffd500
	s_add_i32 s33, s5, s3
	s_add_i32 s3, s4, 0x56
	s_cbranch_execz .LBB0_167
	s_branch .LBB0_168

.LBB0_971:
	s_add_i32 s4, s94, 0x2afff
	s_sub_i32 s6, 0xfffd5001, s94
	s_ashr_i32 s5, s4, 31
	s_max_i32 s4, s4, s6
	v_readlane_b32 s6, v254, 10
	s_mul_hi_u32 s6, s4, s6
	v_readlane_b32 s9, v254, 11
	s_mul_i32 s7, s6, s9
	s_sub_i32 s4, s4, s7
	s_xor_b32 s5, s5, s95
	s_add_i32 s7, s6, 1
	s_sub_i32 s8, s4, s9
	s_cmp_ge_u32 s4, s9
	s_cselect_b32 s6, s7, s6
	s_cselect_b32 s4, s8, s4
	s_add_i32 s7, s6, 1
	s_cmp_ge_u32 s4, s9
	s_cselect_b32 s4, s7, s6
	s_xor_b32 s4, s4, s5
	s_sub_i32 s4, s4, s5
	s_and_b32 s5, s4, 1
	s_add_i32 s4, s5, s4
	s_mul_i32 s6, s4, s86
	s_sub_i32 s5, 0x2b000, s6
	s_min_i32 s4, s5, s4
	s_cmp_lt_i32 s6, 0x2b001
	s_mov_b32 s16, 0
	s_cmp_eq_u32 s16, 0
	s_cbranch_scc1 .LBB0_976
	s_cmp_gt_i32 s6, -1
	s_cbranch_scc0 .LBB0_974
	s_mul_hi_u32 s3, s6, 0x2fa0be83
	s_lshr_b32 s3, s3, 11
	s_mul_i32 s4, s3, 0xffffd500
	s_add_i32 s33, s4, s6
	s_addk_i32 s3, 0x56
	s_cbranch_execz .LBB0_975
	s_branch .LBB0_976

.LBB0_1074:
	s_waitcnt vmcnt(0)
	s_waitcnt vmcnt(0) lgkmcnt(0)
	s_barrier
	s_mov_b64 s[4:5], exec
	v_readlane_b32 s6, v254, 8
	v_readlane_b32 s7, v254, 9
	s_and_b64 s[6:7], s[4:5], s[6:7]
	s_mov_b64 exec, s[6:7]
	s_cbranch_execz .LBB0_1126
	s_add_i32 s3, 0, 0x20160
	v_mov_b32_e32 v0, s3
	s_waitcnt vmcnt(0) expcnt(0) lgkmcnt(0)
	ds_read_b32 v2, v0
	s_add_i32 s3, 0, 0x20164
	v_mov_b32_e32 v0, s3
	ds_read_b32 v0, v0
	s_waitcnt lgkmcnt(1)
	v_cmp_ne_u32_e32 vcc, 0, v2
	s_cbranch_vccnz .LBB0_1090
	v_readlane_b32 s6, v254, 0
	v_readlane_b32 s7, v254, 1
	s_load_dwordx2 s[10:11], s[6:7], 0x4
	s_load_dword s3, s[0:1], 0xb0
	s_add_u32 s6, s96, 0x4200
	s_addc_u32 s7, s97, 0
	s_add_u32 s8, s96, 0x4400
	s_addc_u32 s9, s97, 0
	s_waitcnt lgkmcnt(0)
	s_mul_i32 s3, s10, s3
	s_add_u32 s10, s96, 0x4500
	s_mul_i32 s3, s3, s11
	s_addc_u32 s11, s97, 0
	s_add_u32 s12, s96, 0x4600
	s_addc_u32 s13, s97, 0
	s_add_u32 s14, s96, 0x4700
	s_addc_u32 s15, s97, 0
	s_add_u32 s16, s96, 0x4800
	s_addc_u32 s17, s97, 0
	s_add_u32 s20, s96, 0x4900
	s_addc_u32 s21, s97, 0
	s_add_u32 s22, s96, 0x4a00
	s_addc_u32 s23, s97, 0
	s_add_u32 s24, s96, 0x4b00
	s_addc_u32 s25, s97, 0
	s_add_u32 s26, s96, 0x4c00
	s_addc_u32 s27, s97, 0
	s_add_u32 s28, s96, 0x4d00
	s_addc_u32 s29, s97, 0
	s_add_u32 s30, s96, 0x4e00
	s_addc_u32 s31, s97, 0
	s_add_u32 s34, s96, 0x4f00
	s_addc_u32 s35, s97, 0
	s_add_u32 s36, s96, 0x5000
	s_addc_u32 s37, s97, 0
	s_add_u32 s38, s96, 0x5100
	s_addc_u32 s39, s97, 0
	s_add_u32 s40, s96, 0x5200
	s_addc_u32 s41, s97, 0
	s_add_u32 s42, s96, 0x5300
	s_addc_u32 s43, s97, 0
	s_mov_b32 s33, 1
	v_mov_b32_e32 v16, 0
	s_branch .LBB0_1078
